# 8-byte global stores write-through too, on top of v24
# speedup vs baseline: 1.0229x; 1.0000x over previous
; template <int MODE> ...
;     for (int m = RPW * gw; m < M_TOK; m += RPW * NGW) {
;         f32x4 xv[RPW][8]; v2u yy[RPW][8];
; #pragma unroll
;         for (int rr = 0; rr < RPW; ++rr) {
;             const float* xr = ((MODE == 0 || xin != nullptr) ? xin : xres) + (size_t)(m + rr) * DM + lane * 4;
; #pragma unroll
;             for (int k = 0; k < 8; ++k) xv[rr][k] = *(const f32x4*)(xr + k * 256);
;     ...
;         if (MODE <= 1) {
;             float rstd[RPW];
; #pragma unroll
;             for (int rr = 0; rr < RPW; ++rr) { float s = 0.f;
; #pragma unroll
;                 for (int k = 0; k < 8; ++k) s += (xv[rr][k][0] * xv[rr][k][0] + xv[rr][k][1] * xv[rr][k][1]) + (xv[rr][k][2] * xv[rr][k][2] + xv[rr][k][3] * xv[rr][k][3]);
.LBB0_137:
	global_load_dwordx4 v[46:49], v[68:69], off offset:-4096 nt
	global_load_dwordx4 v[42:45], v[68:69], off offset:-3072 nt
	global_load_dwordx4 v[38:41], v[68:69], off offset:-2048 nt
	global_load_dwordx4 v[34:37], v[68:69], off offset:-1024 nt
	v_add_co_u32_e32 v70, vcc, 0xffffe000, v68
	global_load_dwordx4 v[54:57], v[68:69], off nt
	global_load_dwordx4 v[50:53], v[68:69], off offset:1024 nt
	global_load_dwordx4 v[62:65], v[68:69], off offset:2048 nt
	global_load_dwordx4 v[58:61], v[68:69], off offset:3072 nt
	v_addc_co_u32_e32 v71, vcc, -1, v69, vcc
	global_load_dwordx4 v[88:91], v[70:71], off nt
	v_add_co_u32_e32 v104, vcc, 0xfffff000, v68
	v_add_co_u32_e64 v72, s[4:5], s16, v66
	s_nop 0
	v_addc_co_u32_e32 v105, vcc, -1, v69, vcc
	v_add_co_u32_e32 v70, vcc, s0, v68
	global_load_dwordx4 v[92:95], v[104:105], off offset:-3072 nt
	global_load_dwordx4 v[96:99], v[104:105], off offset:-2048 nt
	global_load_dwordx4 v[100:103], v[104:105], off offset:-1024 nt
	v_addc_co_u32_e32 v71, vcc, 0, v69, vcc
	global_load_dwordx4 v[104:107], v[70:71], off nt
	global_load_dwordx4 v[108:111], v[70:71], off offset:1024 nt
	global_load_dwordx4 v[112:115], v[70:71], off offset:2048 nt
	global_load_dwordx4 v[116:119], v[70:71], off offset:3072 nt
	v_addc_co_u32_e64 v73, s[4:5], -1, v67, s[4:5]
	v_add_co_u32_e64 v74, s[4:5], s17, v66
	s_add_i32 s8, s8, s10
	s_nop 0
	v_addc_co_u32_e64 v75, s[4:5], -1, v67, s[4:5]
	v_add_co_u32_e64 v76, s[4:5], s18, v66
	s_cmpk_gt_i32 s8, 0x3fff
	s_nop 0
	v_addc_co_u32_e64 v77, s[4:5], -1, v67, s[4:5]
	v_add_co_u32_e64 v78, s[4:5], s19, v66
	v_lshl_add_u64 v[68:69], v[68:69], 0, s[14:15]
	s_nop 0
	v_addc_co_u32_e64 v79, s[4:5], -1, v67, s[4:5]
	v_add_co_u32_e64 v80, s[4:5], s20, v66
	s_waitcnt vmcnt(15)
	v_mul_f32_e32 v70, v47, v47
	v_mul_f32_e32 v71, v49, v49
	s_waitcnt vmcnt(14)
	v_mul_f32_e32 v87, v43, v43
	v_mul_f32_e32 v120, v45, v45
	s_waitcnt vmcnt(13)
	v_mul_f32_e32 v121, v39, v39
	v_mul_f32_e32 v122, v41, v41
	s_waitcnt vmcnt(12)
	v_mul_f32_e32 v123, v35, v35
	v_mul_f32_e32 v124, v37, v37
	s_waitcnt vmcnt(11)
	v_mul_f32_e32 v125, v55, v55
	v_mul_f32_e32 v126, v57, v57
	s_waitcnt vmcnt(10)
	v_mul_f32_e32 v127, v51, v51
	v_mul_f32_e32 v128, v53, v53
	s_waitcnt vmcnt(9)
	v_mul_f32_e32 v129, v63, v63
	v_mul_f32_e32 v130, v65, v65
	v_fmac_f32_e32 v70, v46, v46
	v_fmac_f32_e32 v71, v48, v48
	v_fmac_f32_e32 v87, v42, v42
	v_fmac_f32_e32 v120, v44, v44
	v_fmac_f32_e32 v121, v38, v38
	v_fmac_f32_e32 v122, v40, v40
	v_fmac_f32_e32 v123, v34, v34
	v_fmac_f32_e32 v124, v36, v36
	v_fmac_f32_e32 v125, v54, v54
	v_fmac_f32_e32 v126, v56, v56
	v_fmac_f32_e32 v127, v50, v50
	v_fmac_f32_e32 v128, v52, v52
	v_fmac_f32_e32 v129, v62, v62
	v_fmac_f32_e32 v130, v64, v64
	v_add_f32_e32 v70, v70, v71
	s_waitcnt vmcnt(7)
	v_mul_f32_e32 v71, v89, v89
	v_add_f32_e32 v87, v87, v120
	v_mul_f32_e32 v120, v91, v91
	v_add_f32_e32 v121, v121, v122
	v_add_f32_e32 v122, v123, v124
	v_add_f32_e32 v123, v125, v126
	v_add_f32_e32 v124, v127, v128
	v_mul_f32_e32 v131, v59, v59
	v_mul_f32_e32 v132, v61, v61
	v_add_f32_e32 v125, v129, v130
	v_fmac_f32_e32 v71, v88, v88
	v_fmac_f32_e32 v120, v90, v90
	s_waitcnt vmcnt(6)
	v_mul_f32_e32 v127, v93, v93
	v_mul_f32_e32 v128, v95, v95
	v_add_f32_e32 v123, v123, v124
	v_fmac_f32_e32 v131, v58, v58
	v_fmac_f32_e32 v132, v60, v60
	s_waitcnt vmcnt(5)
	v_mul_f32_e32 v129, v97, v97
	v_mul_f32_e32 v130, v99, v99
	v_add_f32_e32 v71, v71, v120
	v_fmac_f32_e32 v127, v92, v92
	v_fmac_f32_e32 v128, v94, v94
	v_add_f32_e32 v120, v123, v125
	s_waitcnt vmcnt(3)
	v_mul_f32_e32 v123, v105, v105
	v_mul_f32_e32 v124, v107, v107
	v_add_f32_e32 v126, v131, v132
	v_mul_f32_e32 v131, v101, v101
	v_mul_f32_e32 v132, v103, v103
	v_fmac_f32_e32 v129, v96, v96
	v_fmac_f32_e32 v130, v98, v98
	s_waitcnt vmcnt(2)
	v_mul_f32_e32 v125, v109, v109
	v_mul_f32_e32 v133, v111, v111
	v_add_f32_e32 v127, v127, v128
	v_fmac_f32_e32 v123, v104, v104
	v_fmac_f32_e32 v124, v106, v106
	v_fmac_f32_e32 v131, v100, v100
	v_fmac_f32_e32 v132, v102, v102
	s_waitcnt vmcnt(1)
	v_mul_f32_e32 v134, v113, v113
	v_mul_f32_e32 v135, v115, v115
	v_add_f32_e32 v128, v129, v130
	v_add_f32_e32 v120, v120, v126
	v_fmac_f32_e32 v125, v108, v108
	v_fmac_f32_e32 v133, v110, v110
	v_add_f32_e32 v71, v71, v127
	v_add_f32_e32 v123, v123, v124
	s_waitcnt vmcnt(0)
; template <int MODE> ...
;     ...
;                 for (int k = 0; k < 8; ++k) s += (xv[rr][k][0] * xv[rr][k][0] + xv[rr][k][1] * xv[rr][k][1]) + (xv[rr][k][2] * xv[rr][k][2] + xv[rr][k][3] * xv[rr][k][3]);
;                 rstd[rr] = 1.0f / sqrtf(wave_sum(s) * (1.f / DM) + RMS_EPS); }
; #pragma unroll
;             for (int k = 0; k < 8; ++k) { const f32x4 g = *(const f32x4*)(gpre + k * 256 + lane * 4);
; #pragma unroll
;                 for (int rr = 0; rr < RPW; ++rr) { const f32x4 a = xv[rr][k] * rstd[rr] * g;
	v_mul_f32_e32 v136, v117, v117
	v_mul_f32_e32 v137, v119, v119
	v_add_f32_e32 v129, v131, v132
	v_fmac_f32_e32 v134, v112, v112
	v_fmac_f32_e32 v135, v114, v114
	v_add_f32_e32 v124, v125, v133
	v_add_f32_e32 v71, v71, v128
	v_add_f32_e32 v120, v120, v123
	v_fmac_f32_e32 v136, v116, v116
	v_fmac_f32_e32 v137, v118, v118
	v_add_f32_e32 v125, v134, v135
	v_add_f32_e32 v71, v71, v129
	v_add_f32_e32 v120, v120, v124
	v_add_f32_e32 v126, v136, v137
	v_add_f32_e32 v70, v71, v70
	v_add_f32_e32 v71, v120, v125
	v_add_f32_e32 v70, v70, v87
	v_add_f32_e32 v71, v71, v126
	v_add_f32_e32 v70, v70, v121
	v_add_f32_e32 v70, v70, v122
	v_add_f32_dpp v71, v71, v71 quad_perm:[1,0,3,2] row_mask:0xf bank_mask:0xf bound_ctrl:1
	v_addc_co_u32_e64 v81, s[4:5], -1, v67, s[4:5]
	s_nop 0
	v_add_f32_dpp v71, v71, v71 quad_perm:[2,3,0,1] row_mask:0xf bank_mask:0xf bound_ctrl:1
	v_add_f32_dpp v70, v70, v70 quad_perm:[1,0,3,2] row_mask:0xf bank_mask:0xf bound_ctrl:1
	v_add_co_u32_e64 v82, s[4:5], s21, v66
	v_add_f32_dpp v71, v71, v71 row_half_mirror row_mask:0xf bank_mask:0xf bound_ctrl:1
	v_add_f32_dpp v70, v70, v70 quad_perm:[2,3,0,1] row_mask:0xf bank_mask:0xf bound_ctrl:1
	v_addc_co_u32_e64 v83, s[4:5], -1, v67, s[4:5]
	v_add_f32_dpp v71, v71, v71 row_mirror row_mask:0xf bank_mask:0xf bound_ctrl:1
	v_add_f32_dpp v70, v70, v70 row_half_mirror row_mask:0xf bank_mask:0xf bound_ctrl:1
	v_mov_b32_e32 v87, v71
	s_nop 1
	v_permlane16_swap_b32_e32 v71, v87
	v_add_f32_dpp v70, v70, v70 row_mirror row_mask:0xf bank_mask:0xf bound_ctrl:1
	v_mov_b32_e32 v120, v70
	v_add_f32_e32 v71, v71, v87
	s_nop 0
	v_permlane16_swap_b32_e32 v70, v120
	v_mov_b32_e32 v87, v71
	v_add_f32_e32 v70, v70, v120
	s_nop 0
	v_permlane32_swap_b32_e32 v71, v87
	v_mov_b32_e32 v120, v70
	v_add_f32_e32 v71, v71, v87
	s_nop 0
	v_permlane32_swap_b32_e32 v70, v120
	v_fmamk_f32 v71, v71, 0x3a000000, v1
	v_add_co_u32_e64 v84, s[4:5], s22, v66
	v_add_f32_e32 v70, v70, v120
	v_mul_f32_e32 v87, 0x4f800000, v71
	v_cmp_gt_f32_e32 vcc, s1, v71
	v_addc_co_u32_e64 v85, s[4:5], -1, v67, s[4:5]
	v_fmamk_f32 v70, v70, 0x3a000000, v1
	v_cndmask_b32_e32 v71, v71, v87, vcc
	v_mul_f32_e32 v87, 0x4f800000, v70
	v_sqrt_f32_e32 v120, v71
	v_cmp_gt_f32_e64 s[4:5], s1, v70
	v_add_u32_e32 v121, -1, v120
	s_nop 0
	v_cndmask_b32_e64 v70, v70, v87, s[4:5]
	v_sqrt_f32_e32 v87, v70
	v_add_u32_e32 v122, 1, v120
	v_fma_f32 v123, -v121, v120, v71
	v_fma_f32 v124, -v122, v120, v71
	v_add_u32_e32 v125, -1, v87
	v_cmp_ge_f32_e64 s[6:7], 0, v123
	v_add_u32_e32 v126, 1, v87
	v_fma_f32 v123, -v126, v87, v70
	v_cndmask_b32_e64 v120, v120, v121, s[6:7]
	v_cmp_lt_f32_e64 s[6:7], 0, v124
	v_fma_f32 v121, -v125, v87, v70
	s_nop 0
	v_cndmask_b32_e64 v120, v120, v122, s[6:7]
	v_cmp_ge_f32_e64 s[6:7], 0, v121
	v_mul_f32_e32 v121, 0x37800000, v120
	v_cndmask_b32_e32 v120, v120, v121, vcc
	v_cndmask_b32_e64 v87, v87, v125, s[6:7]
	v_cmp_lt_f32_e64 s[6:7], 0, v123
	v_cmp_class_f32_e32 vcc, v71, v86
	s_nop 0
	v_cndmask_b32_e64 v87, v87, v126, s[6:7]
	v_mul_f32_e32 v121, 0x37800000, v87
	v_cndmask_b32_e32 v71, v120, v71, vcc
	v_cndmask_b32_e64 v87, v87, v121, s[4:5]
	v_cmp_class_f32_e32 vcc, v70, v86
	v_div_scale_f32 v120, s[4:5], v71, v71, 1.0
	s_nop 0
	v_cndmask_b32_e32 v70, v87, v70, vcc
	v_rcp_f32_e32 v87, v120
	v_div_scale_f32 v122, s[6:7], v70, v70, 1.0
	v_rcp_f32_e32 v124, v122
	v_fma_f32 v125, -v120, v87, 1.0
	v_div_scale_f32 v121, s[4:5], 1.0, v71, 1.0
	v_fmac_f32_e32 v87, v125, v87
	v_fma_f32 v125, -v122, v124, 1.0
	v_div_scale_f32 v123, vcc, 1.0, v70, 1.0
	v_mul_f32_e32 v126, v121, v87
	v_fmac_f32_e32 v124, v125, v124
	v_fma_f32 v125, -v120, v126, v121
	v_mul_f32_e32 v127, v123, v124
	v_fmac_f32_e32 v126, v125, v87
	v_fma_f32 v125, -v122, v127, v123
	v_fmac_f32_e32 v127, v125, v124
	v_fma_f32 v120, -v120, v126, v121
	v_fma_f32 v121, -v122, v127, v123
	v_div_fmas_f32 v121, v121, v124, v127
	s_mov_b64 vcc, s[4:5]
	v_div_fixup_f32 v70, v121, v70, 1.0
	v_div_fmas_f32 v87, v120, v87, v126
	v_pk_mul_f32 v[88:89], v[88:89], v[70:71] op_sel_hi:[1,0]
	v_pk_mul_f32 v[90:91], v[90:91], v[70:71] op_sel_hi:[1,0]
	v_pk_mul_f32 v[92:93], v[92:93], v[70:71] op_sel_hi:[1,0]
	v_pk_mul_f32 v[94:95], v[94:95], v[70:71] op_sel_hi:[1,0]
	v_pk_mul_f32 v[96:97], v[96:97], v[70:71] op_sel_hi:[1,0]
	v_pk_mul_f32 v[98:99], v[98:99], v[70:71] op_sel_hi:[1,0]
	v_pk_mul_f32 v[100:101], v[100:101], v[70:71] op_sel_hi:[1,0]
	v_pk_mul_f32 v[102:103], v[102:103], v[70:71] op_sel_hi:[1,0]
	v_pk_mul_f32 v[46:47], v[46:47], v[70:71] op_sel_hi:[1,0]
	v_pk_mul_f32 v[48:49], v[48:49], v[70:71] op_sel_hi:[1,0]
	v_pk_mul_f32 v[42:43], v[42:43], v[70:71] op_sel_hi:[1,0]
	v_pk_mul_f32 v[44:45], v[44:45], v[70:71] op_sel_hi:[1,0]
	v_pk_mul_f32 v[38:39], v[38:39], v[70:71] op_sel_hi:[1,0]
	v_pk_mul_f32 v[40:41], v[40:41], v[70:71] op_sel_hi:[1,0]
	v_pk_mul_f32 v[34:35], v[34:35], v[70:71] op_sel_hi:[1,0]
	v_pk_mul_f32 v[36:37], v[36:37], v[70:71] op_sel_hi:[1,0]
	v_div_fixup_f32 v70, v87, v71, 1.0
	v_pk_mul_f32 v[54:55], v[54:55], v[70:71] op_sel_hi:[1,0]
	v_pk_mul_f32 v[56:57], v[56:57], v[70:71] op_sel_hi:[1,0]
	v_pk_mul_f32 v[88:89], v[2:3], v[88:89]
	v_pk_mul_f32 v[90:91], v[4:5], v[90:91]
	v_pk_mul_f32 v[92:93], v[6:7], v[92:93]
	v_pk_mul_f32 v[38:39], v[26:27], v[38:39]
	v_pk_mul_f32 v[40:41], v[28:29], v[40:41]
	v_pk_mul_f32 v[34:35], v[30:31], v[34:35]
	v_pk_mul_f32 v[36:37], v[32:33], v[36:37]
	v_pk_mul_f32 v[50:51], v[50:51], v[70:71] op_sel_hi:[1,0]
	v_pk_mul_f32 v[52:53], v[52:53], v[70:71] op_sel_hi:[1,0]
	v_pk_mul_f32 v[62:63], v[62:63], v[70:71] op_sel_hi:[1,0]
	v_pk_mul_f32 v[64:65], v[64:65], v[70:71] op_sel_hi:[1,0]
	v_pk_mul_f32 v[58:59], v[58:59], v[70:71] op_sel_hi:[1,0]
; __device__ __forceinline__ unsigned pk2(float lo, float hi) { return f2bf(lo) | (f2bf(hi) << 16); }
; template <int MODE> ...
;     ...
;                 for (int rr = 0; rr < RPW; ++rr) { const f32x4 a = xv[rr][k] * rstd[rr] * g;
;                     v2u o; o.x = pk2(a[0], a[1]); o.y = pk2(a[2], a[3]);
	v_pk_mul_f32 v[60:61], v[60:61], v[70:71] op_sel_hi:[1,0]
	v_pk_mul_f32 v[104:105], v[104:105], v[70:71] op_sel_hi:[1,0]
	v_pk_mul_f32 v[106:107], v[106:107], v[70:71] op_sel_hi:[1,0]
	v_pk_mul_f32 v[108:109], v[108:109], v[70:71] op_sel_hi:[1,0]
	v_pk_mul_f32 v[110:111], v[110:111], v[70:71] op_sel_hi:[1,0]
	v_pk_mul_f32 v[112:113], v[112:113], v[70:71] op_sel_hi:[1,0]
	v_pk_mul_f32 v[114:115], v[114:115], v[70:71] op_sel_hi:[1,0]
	v_pk_mul_f32 v[116:117], v[116:117], v[70:71] op_sel_hi:[1,0]
	v_pk_mul_f32 v[70:71], v[118:119], v[70:71] op_sel_hi:[1,0]
	v_pk_mul_f32 v[94:95], v[8:9], v[94:95]
	v_pk_mul_f32 v[96:97], v[10:11], v[96:97]
	v_pk_mul_f32 v[98:99], v[12:13], v[98:99]
	v_pk_mul_f32 v[100:101], v[14:15], v[100:101]
	v_pk_mul_f32 v[102:103], v[16:17], v[102:103]
	v_pk_mul_f32 v[46:47], v[18:19], v[46:47]
	v_pk_mul_f32 v[48:49], v[20:21], v[48:49]
	v_pk_mul_f32 v[42:43], v[22:23], v[42:43]
	v_pk_mul_f32 v[44:45], v[24:25], v[44:45]
	v_bfe_u32 v87, v88, 16, 1
	v_bfe_u32 v118, v89, 16, 1
	v_bfe_u32 v119, v90, 16, 1
	v_bfe_u32 v120, v91, 16, 1
	v_bfe_u32 v121, v92, 16, 1
	v_bfe_u32 v142, v39, 16, 1
	v_bfe_u32 v143, v40, 16, 1
	v_bfe_u32 v146, v35, 16, 1
	v_bfe_u32 v147, v36, 16, 1
	v_bfe_u32 v148, v37, 16, 1
	v_pk_mul_f32 v[54:55], v[2:3], v[54:55]
	v_pk_mul_f32 v[56:57], v[4:5], v[56:57]
	v_bfe_u32 v122, v93, 16, 1
	v_bfe_u32 v123, v94, 16, 1
	v_bfe_u32 v124, v95, 16, 1
	v_bfe_u32 v125, v96, 16, 1
	v_bfe_u32 v126, v97, 16, 1
	v_bfe_u32 v127, v98, 16, 1
	v_bfe_u32 v128, v99, 16, 1
	v_bfe_u32 v129, v100, 16, 1
	v_bfe_u32 v130, v101, 16, 1
	v_bfe_u32 v131, v102, 16, 1
	v_bfe_u32 v132, v103, 16, 1
	v_bfe_u32 v133, v46, 16, 1
	v_bfe_u32 v135, v48, 16, 1
	v_bfe_u32 v137, v42, 16, 1
	v_bfe_u32 v138, v43, 16, 1
	v_bfe_u32 v139, v44, 16, 1
	v_bfe_u32 v141, v38, 16, 1
	v_bfe_u32 v144, v41, 16, 1
	v_bfe_u32 v145, v34, 16, 1
	v_pk_mul_f32 v[50:51], v[6:7], v[50:51]
	v_pk_mul_f32 v[52:53], v[8:9], v[52:53]
	v_pk_mul_f32 v[62:63], v[10:11], v[62:63]
	v_pk_mul_f32 v[64:65], v[12:13], v[64:65]
	v_pk_mul_f32 v[58:59], v[14:15], v[58:59]
	v_pk_mul_f32 v[60:61], v[16:17], v[60:61]
	v_pk_mul_f32 v[104:105], v[18:19], v[104:105]
	v_pk_mul_f32 v[106:107], v[20:21], v[106:107]
	v_pk_mul_f32 v[108:109], v[22:23], v[108:109]
	v_pk_mul_f32 v[110:111], v[24:25], v[110:111]
	v_pk_mul_f32 v[112:113], v[26:27], v[112:113]
	v_pk_mul_f32 v[114:115], v[28:29], v[114:115]
	v_pk_mul_f32 v[116:117], v[30:31], v[116:117]
	v_pk_mul_f32 v[70:71], v[32:33], v[70:71]
	v_add3_u32 v87, v88, v87, s9
	v_add3_u32 v88, v89, v118, s9
	v_add3_u32 v89, v90, v119, s9
	v_add3_u32 v90, v91, v120, s9
	v_add3_u32 v91, v92, v121, s9
	v_add3_u32 v118, v39, v142, s9
	v_add3_u32 v39, v40, v143, s9
	v_add3_u32 v120, v35, v146, s9
	v_add3_u32 v35, v36, v147, s9
	v_add3_u32 v121, v37, v148, s9
	v_bfe_u32 v36, v54, 16, 1
	v_bfe_u32 v37, v55, 16, 1
	v_bfe_u32 v40, v56, 16, 1
	v_bfe_u32 v134, v47, 16, 1
	v_bfe_u32 v136, v49, 16, 1
	v_bfe_u32 v140, v45, 16, 1
	v_add3_u32 v92, v93, v122, s9
	v_add3_u32 v93, v94, v123, s9
	v_add3_u32 v94, v95, v124, s9
	v_add3_u32 v95, v96, v125, s9
	v_add3_u32 v96, v97, v126, s9
	v_add3_u32 v97, v98, v127, s9
	v_add3_u32 v98, v99, v128, s9
	v_add3_u32 v99, v100, v129, s9
	v_add3_u32 v100, v101, v130, s9
	v_add3_u32 v101, v102, v131, s9
	v_add3_u32 v102, v103, v132, s9
	v_add3_u32 v46, v46, v133, s9
	v_add3_u32 v48, v48, v135, s9
	v_add3_u32 v42, v42, v137, s9
	v_add3_u32 v103, v43, v138, s9
	v_add3_u32 v43, v44, v139, s9
	v_add3_u32 v38, v38, v141, s9
	v_add3_u32 v119, v41, v144, s9
	v_add3_u32 v34, v34, v145, s9
	v_bfe_u32 v41, v57, 16, 1
	v_bfe_u32 v44, v50, 16, 1
	v_bfe_u32 v122, v51, 16, 1
	v_bfe_u32 v123, v52, 16, 1
	v_bfe_u32 v125, v62, 16, 1
	v_bfe_u32 v127, v64, 16, 1
	v_bfe_u32 v129, v58, 16, 1
	v_bfe_u32 v131, v60, 16, 1
	v_bfe_u32 v133, v104, 16, 1
	v_bfe_u32 v135, v106, 16, 1
	v_bfe_u32 v137, v108, 16, 1
	v_bfe_u32 v139, v110, 16, 1
	v_bfe_u32 v141, v112, 16, 1
	v_bfe_u32 v143, v114, 16, 1
	v_bfe_u32 v145, v116, 16, 1
	v_bfe_u32 v147, v70, 16, 1
	v_add3_u32 v54, v54, v36, s9
	v_add3_u32 v55, v55, v37, s9
	v_add3_u32 v56, v56, v40, s9
	v_lshrrev_b32_e32 v36, 16, v87
	v_lshrrev_b32_e32 v37, 16, v89
	v_add3_u32 v47, v47, v134, s9
	v_add3_u32 v49, v49, v136, s9
	v_add3_u32 v45, v45, v140, s9
	v_bfe_u32 v124, v53, 16, 1
	v_bfe_u32 v126, v63, 16, 1
; __device__ __forceinline__ unsigned pk2(float lo, float hi) { return f2bf(lo) | (f2bf(hi) << 16); }
; template <int MODE> ...
;     ...
;                     v2u o; o.x = pk2(a[0], a[1]); o.y = pk2(a[2], a[3]);
;                     *(v2u*)(h + ((size_t)(k * 4 + (lane >> 4)) * M_TOK + (m + rr)) * 64 + (lane & 15) * 4) = o; } }
	v_bfe_u32 v128, v65, 16, 1
	v_bfe_u32 v130, v59, 16, 1
	v_bfe_u32 v132, v61, 16, 1
	v_bfe_u32 v134, v105, 16, 1
	v_bfe_u32 v136, v107, 16, 1
	v_bfe_u32 v138, v109, 16, 1
	v_bfe_u32 v140, v111, 16, 1
	v_bfe_u32 v142, v113, 16, 1
	v_bfe_u32 v144, v115, 16, 1
	v_bfe_u32 v146, v117, 16, 1
	v_bfe_u32 v148, v71, 16, 1
	v_add3_u32 v57, v57, v41, s9
	v_add3_u32 v50, v50, v44, s9
	v_add3_u32 v51, v51, v122, s9
	v_add3_u32 v52, v52, v123, s9
	v_add3_u32 v62, v62, v125, s9
	v_add3_u32 v64, v64, v127, s9
	v_add3_u32 v58, v58, v129, s9
	v_add3_u32 v60, v60, v131, s9
	v_add3_u32 v104, v104, v133, s9
	v_add3_u32 v106, v106, v135, s9
	v_add3_u32 v108, v108, v137, s9
	v_add3_u32 v110, v110, v139, s9
	v_add3_u32 v112, v112, v141, s9
	v_add3_u32 v114, v114, v143, s9
	v_add3_u32 v116, v116, v145, s9
	v_add3_u32 v70, v70, v147, s9
	v_lshrrev_b32_e32 v40, 16, v91
	v_lshrrev_b32_e32 v41, 16, v93
	v_lshrrev_b32_e32 v44, 16, v95
	v_lshrrev_b32_e32 v87, 16, v97
	v_lshrrev_b32_e32 v89, 16, v99
	v_lshrrev_b32_e32 v91, 16, v101
	v_lshrrev_b32_e32 v46, 16, v46
	v_lshrrev_b32_e32 v48, 16, v48
	v_lshrrev_b32_e32 v93, 16, v42
	v_lshrrev_b32_e32 v95, 16, v43
	v_lshrrev_b32_e32 v97, 16, v38
	v_lshrrev_b32_e32 v99, 16, v39
	v_lshrrev_b32_e32 v101, 16, v34
	v_lshrrev_b32_e32 v122, 16, v35
	v_and_or_b32 v34, v88, s11, v36
	v_and_or_b32 v35, v90, s11, v37
	v_lshrrev_b32_e32 v54, 16, v54
	v_lshrrev_b32_e32 v56, 16, v56
	v_add3_u32 v53, v53, v124, s9
	v_add3_u32 v63, v63, v126, s9
	v_add3_u32 v65, v65, v128, s9
	v_add3_u32 v59, v59, v130, s9
	v_add3_u32 v61, v61, v132, s9
	v_add3_u32 v105, v105, v134, s9
	v_add3_u32 v107, v107, v136, s9
	v_add3_u32 v109, v109, v138, s9
	v_add3_u32 v111, v111, v140, s9
	v_add3_u32 v113, v113, v142, s9
	v_add3_u32 v115, v115, v144, s9
	v_add3_u32 v117, v117, v146, s9
	v_add3_u32 v71, v71, v148, s9
	v_and_or_b32 v36, v92, s11, v40
	v_and_or_b32 v37, v94, s11, v41
	v_and_or_b32 v38, v96, s11, v44
	v_and_or_b32 v39, v98, s11, v87
	v_and_or_b32 v40, v100, s11, v89
	v_and_or_b32 v41, v102, s11, v91
	v_and_or_b32 v42, v47, s11, v46
	v_and_or_b32 v43, v49, s11, v48
	v_and_or_b32 v44, v103, s11, v93
	v_and_or_b32 v45, v45, s11, v95
	v_and_or_b32 v46, v118, s11, v97
	v_and_or_b32 v47, v119, s11, v99
	v_and_or_b32 v48, v120, s11, v101
	v_and_or_b32 v49, v121, s11, v122
	v_lshrrev_b32_e32 v50, 16, v50
	v_lshrrev_b32_e32 v52, 16, v52
	v_lshrrev_b32_e32 v62, 16, v62
	v_lshrrev_b32_e32 v64, 16, v64
	v_lshrrev_b32_e32 v58, 16, v58
	v_lshrrev_b32_e32 v60, 16, v60
	v_lshrrev_b32_e32 v87, 16, v104
	v_lshrrev_b32_e32 v88, 16, v106
	v_lshrrev_b32_e32 v89, 16, v108
	v_lshrrev_b32_e32 v90, 16, v110
	v_lshrrev_b32_e32 v91, 16, v112
	v_lshrrev_b32_e32 v92, 16, v114
	v_lshrrev_b32_e32 v93, 16, v116
	v_lshrrev_b32_e32 v70, 16, v70
	global_store_dwordx2 v[72:73], v[34:35], off offset:-128 sc0 sc1
	v_and_or_b32 v34, v55, s11, v54
	v_and_or_b32 v35, v57, s11, v56
	global_store_dwordx2 v[74:75], v[36:37], off offset:-128 sc0 sc1
	v_and_or_b32 v36, v51, s11, v50
	v_and_or_b32 v37, v53, s11, v52
	global_store_dwordx2 v[76:77], v[38:39], off offset:-128 sc0 sc1
	v_and_or_b32 v38, v63, s11, v62
	v_and_or_b32 v39, v65, s11, v64
	global_store_dwordx2 v[78:79], v[40:41], off offset:-128 sc0 sc1
	v_and_or_b32 v40, v59, s11, v58
	v_and_or_b32 v41, v61, s11, v60
	global_store_dwordx2 v[80:81], v[42:43], off offset:-128 sc0 sc1
	v_and_or_b32 v42, v105, s11, v87
	v_and_or_b32 v43, v107, s11, v88
	global_store_dwordx2 v[82:83], v[44:45], off offset:-128 sc0 sc1
	v_and_or_b32 v44, v109, s11, v89
	v_and_or_b32 v45, v111, s11, v90
	global_store_dwordx2 v[84:85], v[46:47], off offset:-128 sc0 sc1
	v_and_or_b32 v46, v113, s11, v91
	v_and_or_b32 v47, v115, s11, v92
	global_store_dwordx2 v[66:67], v[48:49], off offset:-128 sc0 sc1
	v_and_or_b32 v48, v117, s11, v93
	v_and_or_b32 v49, v71, s11, v70
	global_store_dwordx2 v[72:73], v[34:35], off sc0 sc1
	global_store_dwordx2 v[74:75], v[36:37], off sc0 sc1
	global_store_dwordx2 v[76:77], v[38:39], off sc0 sc1
	global_store_dwordx2 v[78:79], v[40:41], off sc0 sc1
	global_store_dwordx2 v[80:81], v[42:43], off sc0 sc1
	global_store_dwordx2 v[82:83], v[44:45], off sc0 sc1
	global_store_dwordx2 v[84:85], v[46:47], off sc0 sc1
	global_store_dwordx2 v[66:67], v[48:49], off sc0 sc1
	v_lshl_add_u64 v[66:67], v[66:67], 0, s[12:13]
	s_cbranch_scc0 .LBB0_137

; __device__ __forceinline__ float bf2f(unsigned h) { return __uint_as_float(h << 16); }
; template <int MODE> ...
;     for (int m = RPW * gw; m < M_TOK; m += RPW * NGW) {
;         f32x4 xv[RPW][8]; v2u yy[RPW][8];
; #pragma unroll
;         for (int rr = 0; rr < RPW; ++rr) {
;             const float* xr = ((MODE == 0 || xin != nullptr) ? xin : xres) + (size_t)(m + rr) * DM + lane * 4;
; #pragma unroll
;             for (int k = 0; k < 8; ++k) xv[rr][k] = *(const f32x4*)(xr + k * 256);
;             if (MODE >= 1) { const bf16_t* yr = y + (size_t)(m + rr) * 256 + lane * 4;
; #pragma unroll
;                 for (int k = 0; k < 8; ++k) yy[rr][k] = *(const v2u*)(yr + (size_t)k * ((size_t)M_TOK * 256)); }
;         }
;         if (MODE >= 1) {
;             float rstd[RPW];
; #pragma unroll
;             for (int rr = 0; rr < RPW; ++rr) { float s = 0.f;
; #pragma unroll
;                 for (int k = 0; k < 8; ++k)
; #pragma unroll
;                     for (int e = 0; e < 2; ++e) { const float a = bf2f(yy[rr][k][e] & 0xffffu), b = bf2f(yy[rr][k][e] >> 16); s += a * a + b * b; }
;                 rstd[rr] = 1.0f / sqrtf(wave_sum(s) * (1.f / DM) + RMS_EPS); }
.LBB0_225:
	v_lshl_add_u64 v[98:99], s[64:65], 0, v[146:147]
	v_add_co_u32_e32 v66, vcc, 0x1000, v98
	v_lshl_add_u64 v[100:101], v[150:151], 0, s[46:47]
	s_nop 0
	v_addc_co_u32_e32 v67, vcc, 0, v99, vcc
	v_add_co_u32_e32 v114, vcc, 0x8800000, v100
	global_load_dwordx4 v[94:97], v[98:99], off nt
	global_load_dwordx4 v[90:93], v[98:99], off offset:1024 nt
	global_load_dwordx4 v[86:89], v[98:99], off offset:2048 nt
	global_load_dwordx4 v[82:85], v[98:99], off offset:3072 nt
	v_addc_co_u32_e32 v115, vcc, 0, v101, vcc
	global_load_dwordx4 v[78:81], v[66:67], off nt
	global_load_dwordx4 v[74:77], v[66:67], off offset:1024 nt
	global_load_dwordx4 v[70:73], v[66:67], off offset:2048 nt
	s_nop 0
	global_load_dwordx4 v[66:69], v[66:67], off offset:3072 nt
	v_add_co_u32_e32 v118, vcc, 0x9000000, v100
	global_load_dwordx2 v[116:117], v[114:115], off nt
	s_nop 0
	v_addc_co_u32_e32 v119, vcc, 0, v101, vcc
	global_load_dwordx2 v[120:121], v[118:119], off nt
	v_add_co_u32_e32 v122, vcc, 0x9800000, v100
	s_add_i32 s42, s42, s18
	s_nop 0
	v_addc_co_u32_e32 v123, vcc, 0, v101, vcc
	global_load_dwordx2 v[124:125], v[122:123], off nt
	v_add_co_u32_e32 v126, vcc, 0xa000000, v100
	v_lshl_add_u64 v[150:151], v[150:151], 0, s[22:23]
	s_nop 0
	v_addc_co_u32_e32 v127, vcc, 0, v101, vcc
	global_load_dwordx2 v[128:129], v[126:127], off nt
	v_add_co_u32_e32 v152, vcc, 0xa800000, v100
	s_waitcnt vmcnt(3)
	v_lshlrev_b32_e32 v168, 16, v116
	v_addc_co_u32_e32 v153, vcc, 0, v101, vcc
	global_load_dwordx2 v[154:155], v[152:153], off nt
	v_add_co_u32_e32 v156, vcc, 0xb000000, v100
	v_and_b32_e32 v169, 0xffff0000, v116
	s_nop 0
	v_addc_co_u32_e32 v157, vcc, 0, v101, vcc
	global_load_dwordx2 v[158:159], v[156:157], off nt
	v_add_co_u32_e32 v160, vcc, 0xb800000, v100
	v_lshlrev_b32_e32 v116, 16, v117
	s_nop 0
	v_addc_co_u32_e32 v161, vcc, 0, v101, vcc
	global_load_dwordx2 v[162:163], v[160:161], off nt
	v_add_co_u32_e32 v164, vcc, 0xc000000, v100
	v_and_b32_e32 v117, 0xffff0000, v117
	s_nop 0
	v_addc_co_u32_e32 v165, vcc, 0, v101, vcc
	global_load_dwordx2 v[166:167], v[164:165], off nt
	v_add_co_u32_e32 v100, vcc, s31, v98
	v_mul_f32_e32 v1, v169, v169
	s_nop 0
	v_addc_co_u32_e32 v101, vcc, 0, v99, vcc
	v_add_co_u32_e32 v130, vcc, s33, v98
	v_mul_f32_e32 v170, v117, v117
	s_nop 0
	v_addc_co_u32_e32 v131, vcc, 0, v99, vcc
	global_load_dwordx4 v[110:113], v[130:131], off offset:-4096 nt
	global_load_dwordx4 v[106:109], v[100:101], off offset:1024 nt
	global_load_dwordx4 v[102:105], v[100:101], off offset:2048 nt
	s_nop 0
	global_load_dwordx4 v[98:101], v[100:101], off offset:3072 nt
	s_nop 0
	global_load_dwordx4 v[142:145], v[130:131], off nt
	global_load_dwordx4 v[138:141], v[130:131], off offset:1024 nt
	global_load_dwordx4 v[134:137], v[130:131], off offset:2048 nt
	s_nop 0
	global_load_dwordx4 v[130:133], v[130:131], off offset:3072 nt
	s_nop 0
	global_load_dwordx2 v[114:115], v[114:115], off offset:512 nt
	s_nop 0
	global_load_dwordx2 v[118:119], v[118:119], off offset:512 nt
	s_nop 0
	global_load_dwordx2 v[122:123], v[122:123], off offset:512 nt
	s_nop 0
	global_load_dwordx2 v[126:127], v[126:127], off offset:512 nt
	s_nop 0
	global_load_dwordx2 v[152:153], v[152:153], off offset:512 nt
	s_nop 0
	global_load_dwordx2 v[156:157], v[156:157], off offset:512 nt
	s_nop 0
	global_load_dwordx2 v[160:161], v[160:161], off offset:512 nt
	s_nop 0
	global_load_dwordx2 v[164:165], v[164:165], off offset:512 nt
	v_fmac_f32_e32 v1, v168, v168
	v_fmac_f32_e32 v170, v116, v116
	s_waitcnt vmcnt(22)
	v_and_b32_e32 v171, 0xffff0000, v120
	v_add_f32_e32 v1, v1, v170
	v_lshlrev_b32_e32 v170, 16, v120
	v_mul_f32_e32 v120, v171, v171
	v_fmac_f32_e32 v120, v170, v170
	v_add_f32_e32 v1, v1, v120
	v_lshlrev_b32_e32 v120, 16, v121
	v_and_b32_e32 v121, 0xffff0000, v121
	v_mul_f32_e32 v172, v121, v121
	v_fmac_f32_e32 v172, v120, v120
	s_waitcnt vmcnt(21)
	v_and_b32_e32 v173, 0xffff0000, v124
	v_add_f32_e32 v1, v172, v1
	v_lshlrev_b32_e32 v172, 16, v124
	v_mul_f32_e32 v124, v173, v173
	v_fmac_f32_e32 v124, v172, v172
	v_and_b32_e32 v175, 0xffff0000, v125
	v_add_f32_e32 v1, v124, v1
	v_lshlrev_b32_e32 v174, 16, v125
	v_mul_f32_e32 v124, v175, v175
	v_fmac_f32_e32 v124, v174, v174
	s_waitcnt vmcnt(20)
	v_and_b32_e32 v177, 0xffff0000, v128
	v_add_f32_e32 v1, v124, v1
	v_lshlrev_b32_e32 v176, 16, v128
	v_mul_f32_e32 v124, v177, v177
	v_fmac_f32_e32 v124, v176, v176
	v_and_b32_e32 v179, 0xffff0000, v129
	v_add_f32_e32 v1, v124, v1
	v_lshlrev_b32_e32 v178, 16, v129
	v_mul_f32_e32 v124, v179, v179
	v_fmac_f32_e32 v124, v178, v178
	v_add_f32_e32 v1, v124, v1
	s_waitcnt vmcnt(19)
	v_and_b32_e32 v181, 0xffff0000, v154
	v_lshlrev_b32_e32 v180, 16, v154
	v_mul_f32_e32 v124, v181, v181
	v_fmac_f32_e32 v124, v180, v180
	v_lshlrev_b32_e32 v154, 16, v155
	v_and_b32_e32 v155, 0xffff0000, v155
	v_add_f32_e32 v1, v124, v1
	v_mul_f32_e32 v124, v155, v155
	v_fmac_f32_e32 v124, v154, v154
	s_waitcnt vmcnt(18)
	v_and_b32_e32 v183, 0xffff0000, v158
	v_add_f32_e32 v1, v124, v1
	v_lshlrev_b32_e32 v182, 16, v158
	v_mul_f32_e32 v124, v183, v183
	v_fmac_f32_e32 v124, v182, v182
	v_lshlrev_b32_e32 v158, 16, v159
	v_and_b32_e32 v159, 0xffff0000, v159
	v_add_f32_e32 v1, v124, v1
	v_mul_f32_e32 v124, v159, v159
	v_fmac_f32_e32 v124, v158, v158
	s_waitcnt vmcnt(17)
	v_and_b32_e32 v185, 0xffff0000, v162
	v_add_f32_e32 v1, v124, v1
	v_lshlrev_b32_e32 v184, 16, v162
	v_mul_f32_e32 v124, v185, v185
	v_fmac_f32_e32 v124, v184, v184
	v_lshlrev_b32_e32 v162, 16, v163
	v_and_b32_e32 v163, 0xffff0000, v163
	v_add_f32_e32 v1, v124, v1
	v_mul_f32_e32 v124, v163, v163
	v_fmac_f32_e32 v124, v162, v162
	s_waitcnt vmcnt(16)
; __device__ __forceinline__ float bf2f(unsigned h) { return __uint_as_float(h << 16); }
; template <int MODE> ...
;     ...
;             for (int rr = 0; rr < RPW; ++rr) { float s = 0.f;
; #pragma unroll
;                 for (int k = 0; k < 8; ++k)
; #pragma unroll
;                     for (int e = 0; e < 2; ++e) { const float a = bf2f(yy[rr][k][e] & 0xffffu), b = bf2f(yy[rr][k][e] >> 16); s += a * a + b * b; }
;                 rstd[rr] = 1.0f / sqrtf(wave_sum(s) * (1.f / DM) + RMS_EPS); }
	v_and_b32_e32 v187, 0xffff0000, v166
	v_add_f32_e32 v1, v124, v1
	v_lshlrev_b32_e32 v186, 16, v166
	v_mul_f32_e32 v124, v187, v187
	v_fmac_f32_e32 v124, v186, v186
	v_lshlrev_b32_e32 v166, 16, v167
	v_and_b32_e32 v167, 0xffff0000, v167
	v_add_f32_e32 v1, v124, v1
	v_mul_f32_e32 v124, v167, v167
	v_fmac_f32_e32 v124, v166, v166
	v_add_f32_e32 v1, v124, v1
	s_waitcnt vmcnt(6)
	v_and_b32_e32 v191, 0xffff0000, v118
	v_lshlrev_b32_e32 v190, 16, v118
	v_add_f32_dpp v1, v1, v1 quad_perm:[1,0,3,2] row_mask:0xf bank_mask:0xf bound_ctrl:1
	v_mul_f32_e32 v118, v191, v191
	v_fmac_f32_e32 v118, v190, v190
	v_add_f32_dpp v1, v1, v1 quad_perm:[2,3,0,1] row_mask:0xf bank_mask:0xf bound_ctrl:1
	v_and_b32_e32 v193, 0xffff0000, v119
	v_lshlrev_b32_e32 v192, 16, v119
	v_add_f32_dpp v1, v1, v1 row_half_mirror row_mask:0xf bank_mask:0xf bound_ctrl:1
	s_waitcnt vmcnt(5)
	v_and_b32_e32 v195, 0xffff0000, v122
	v_lshlrev_b32_e32 v194, 16, v122
	v_add_f32_dpp v1, v1, v1 row_mirror row_mask:0xf bank_mask:0xf bound_ctrl:1
	v_mov_b32_e32 v124, v1
	s_nop 1
	v_permlane16_swap_b32_e32 v1, v124
	v_add_f32_e32 v1, v1, v124
	v_mov_b32_e32 v124, v1
	s_nop 1
	v_permlane32_swap_b32_e32 v1, v124
	v_add_f32_e32 v1, v1, v124
	v_fmamk_f32 v1, v1, 0x3a000000, v218
	v_cmp_gt_f32_e32 vcc, s30, v1
	v_mul_f32_e32 v124, 0x4f800000, v1
	v_and_b32_e32 v197, 0xffff0000, v123
	v_cndmask_b32_e32 v1, v1, v124, vcc
	v_sqrt_f32_e32 v124, v1
	v_lshlrev_b32_e32 v196, 16, v123
	s_waitcnt vmcnt(4)
	v_and_b32_e32 v199, 0xffff0000, v126
	v_lshlrev_b32_e32 v198, 16, v126
	v_add_u32_e32 v125, -1, v124
	v_fma_f32 v128, -v125, v124, v1
	v_cmp_ge_f32_e64 s[40:41], 0, v128
	v_add_u32_e32 v128, 1, v124
	v_and_b32_e32 v201, 0xffff0000, v127
	v_cndmask_b32_e64 v125, v124, v125, s[40:41]
	v_fma_f32 v124, -v128, v124, v1
	v_cmp_lt_f32_e64 s[40:41], 0, v124
	v_lshlrev_b32_e32 v200, 16, v127
	s_waitcnt vmcnt(3)
	v_and_b32_e32 v203, 0xffff0000, v152
	v_cndmask_b32_e64 v124, v125, v128, s[40:41]
	v_mul_f32_e32 v125, 0x37800000, v124
	v_cndmask_b32_e32 v124, v124, v125, vcc
	v_cmp_class_f32_e32 vcc, v1, v215
	v_lshlrev_b32_e32 v202, 16, v152
	v_lshlrev_b32_e32 v152, 16, v153
	v_cndmask_b32_e32 v1, v124, v1, vcc
	v_div_scale_f32 v124, s[0:1], v1, v1, 1.0
	v_rcp_f32_e32 v125, v124
	v_and_b32_e32 v153, 0xffff0000, v153
	s_waitcnt vmcnt(2)
	v_and_b32_e32 v205, 0xffff0000, v156
	v_lshlrev_b32_e32 v204, 16, v156
	v_fma_f32 v128, -v124, v125, 1.0
	v_fmac_f32_e32 v125, v128, v125
	v_div_scale_f32 v128, vcc, 1.0, v1, 1.0
	v_mul_f32_e32 v129, v128, v125
	v_fma_f32 v188, -v124, v129, v128
	v_fmac_f32_e32 v129, v188, v125
	v_fma_f32 v124, -v124, v129, v128
	v_div_fmas_f32 v124, v124, v125, v129
	v_div_fixup_f32 v188, v124, v1, 1.0
	v_lshlrev_b32_e32 v124, 16, v114
	v_and_b32_e32 v125, 0xffff0000, v114
	v_lshlrev_b32_e32 v114, 16, v115
	v_and_b32_e32 v115, 0xffff0000, v115
	v_mul_f32_e32 v1, v125, v125
	v_mul_f32_e32 v128, v115, v115
	v_fmac_f32_e32 v1, v124, v124
	v_fmac_f32_e32 v128, v114, v114
	v_add_f32_e32 v1, v1, v128
	v_add_f32_e32 v1, v1, v118
	v_mul_f32_e32 v118, v193, v193
	v_fmac_f32_e32 v118, v192, v192
	v_add_f32_e32 v1, v118, v1
	v_mul_f32_e32 v118, v195, v195
	v_fmac_f32_e32 v118, v194, v194
	v_add_f32_e32 v1, v118, v1
	v_mul_f32_e32 v118, v197, v197
	v_fmac_f32_e32 v118, v196, v196
	v_add_f32_e32 v1, v118, v1
	v_mul_f32_e32 v118, v199, v199
	v_fmac_f32_e32 v118, v198, v198
	v_add_f32_e32 v1, v118, v1
	v_mul_f32_e32 v118, v201, v201
	v_fmac_f32_e32 v118, v200, v200
	v_add_f32_e32 v1, v118, v1
	v_mul_f32_e32 v118, v203, v203
	v_fmac_f32_e32 v118, v202, v202
	v_add_f32_e32 v1, v118, v1
	v_mul_f32_e32 v118, v153, v153
	v_fmac_f32_e32 v118, v152, v152
	v_add_f32_e32 v1, v118, v1
	v_mul_f32_e32 v118, v205, v205
	v_fmac_f32_e32 v118, v204, v204
	v_lshlrev_b32_e32 v156, 16, v157
	v_and_b32_e32 v157, 0xffff0000, v157
	v_add_f32_e32 v1, v118, v1
	v_mul_f32_e32 v118, v157, v157
	v_fmac_f32_e32 v118, v156, v156
	s_waitcnt vmcnt(1)
	v_and_b32_e32 v207, 0xffff0000, v160
	v_add_f32_e32 v1, v118, v1
	v_lshlrev_b32_e32 v206, 16, v160
	v_mul_f32_e32 v118, v207, v207
	v_fmac_f32_e32 v118, v206, v206
	v_lshlrev_b32_e32 v160, 16, v161
	v_and_b32_e32 v161, 0xffff0000, v161
	v_add_f32_e32 v1, v118, v1
	v_mul_f32_e32 v118, v161, v161
	v_fmac_f32_e32 v118, v160, v160
	s_waitcnt vmcnt(0)
; __device__ __forceinline__ float bf2f(unsigned h) { return __uint_as_float(h << 16); }
; template <int MODE> ...
;     ...
;                 rstd[rr] = 1.0f / sqrtf(wave_sum(s) * (1.f / DM) + RMS_EPS); }
; #pragma unroll
;             for (int k = 0; k < 8; ++k) { const f32x4 g = *(const f32x4*)(gpost + k * 256 + lane * 4);
; #pragma unroll
;                 for (int rr = 0; rr < RPW; ++rr) { f32x4 yv;
;                     yv[0] = bf2f(yy[rr][k][0] & 0xffffu); yv[1] = bf2f(yy[rr][k][0] >> 16); yv[2] = bf2f(yy[rr][k][1] & 0xffffu); yv[3] = bf2f(yy[rr][k][1] >> 16);
;                     xv[rr][k] += yv * rstd[rr] * g; } }
	v_and_b32_e32 v209, 0xffff0000, v164
	v_add_f32_e32 v1, v118, v1
	v_lshlrev_b32_e32 v208, 16, v164
	v_mul_f32_e32 v118, v209, v209
	v_fmac_f32_e32 v118, v208, v208
	v_lshlrev_b32_e32 v164, 16, v165
	v_and_b32_e32 v165, 0xffff0000, v165
	v_add_f32_e32 v1, v118, v1
	v_mul_f32_e32 v118, v165, v165
	v_fmac_f32_e32 v118, v164, v164
	v_add_f32_e32 v1, v118, v1
	v_pk_mul_f32 v[116:117], v[188:189], v[116:117] op_sel_hi:[0,1]
	v_pk_fma_f32 v[128:129], v[4:5], v[116:117], v[96:97]
	v_add_f32_dpp v1, v1, v1 quad_perm:[1,0,3,2] row_mask:0xf bank_mask:0xf bound_ctrl:1
	s_nop 1
	v_add_f32_dpp v1, v1, v1 quad_perm:[2,3,0,1] row_mask:0xf bank_mask:0xf bound_ctrl:1
	s_nop 1
	v_add_f32_dpp v1, v1, v1 row_half_mirror row_mask:0xf bank_mask:0xf bound_ctrl:1
	s_nop 1
	v_add_f32_dpp v1, v1, v1 row_mirror row_mask:0xf bank_mask:0xf bound_ctrl:1
	v_mov_b32_e32 v118, v1
	s_nop 1
	v_permlane16_swap_b32_e32 v1, v118
	v_add_f32_e32 v1, v1, v118
	v_mov_b32_e32 v118, v1
	s_nop 1
	v_permlane32_swap_b32_e32 v1, v118
	v_add_f32_e32 v1, v1, v118
	v_fmamk_f32 v1, v1, 0x3a000000, v218
	v_cmp_gt_f32_e32 vcc, s30, v1
	v_mul_f32_e32 v118, 0x4f800000, v1
	s_nop 0
	v_cndmask_b32_e32 v1, v1, v118, vcc
	v_sqrt_f32_e32 v118, v1
	s_nop 0
	v_add_u32_e32 v119, -1, v118
	v_fma_f32 v122, -v119, v118, v1
	v_cmp_ge_f32_e64 s[40:41], 0, v122
	v_add_u32_e32 v122, 1, v118
	s_nop 0
	v_cndmask_b32_e64 v119, v118, v119, s[40:41]
	v_fma_f32 v118, -v122, v118, v1
	v_cmp_lt_f32_e64 s[40:41], 0, v118
	s_nop 1
	v_cndmask_b32_e64 v118, v119, v122, s[40:41]
	v_mul_f32_e32 v119, 0x37800000, v118
	v_cndmask_b32_e32 v118, v118, v119, vcc
	v_cmp_class_f32_e32 vcc, v1, v215
	s_nop 1
	v_cndmask_b32_e32 v1, v118, v1, vcc
	v_div_scale_f32 v118, s[0:1], v1, v1, 1.0
	v_rcp_f32_e32 v119, v118
	s_nop 0
	v_fma_f32 v122, -v118, v119, 1.0
	v_fmac_f32_e32 v119, v122, v119
	v_div_scale_f32 v122, vcc, 1.0, v1, 1.0
	v_mul_f32_e32 v123, v122, v119
	v_fma_f32 v126, -v118, v123, v122
	v_fmac_f32_e32 v123, v126, v119
	v_fma_f32 v118, -v118, v123, v122
	v_div_fmas_f32 v118, v118, v119, v123
	v_div_fixup_f32 v210, v118, v1, 1.0
	v_pk_mul_f32 v[118:119], v[188:189], v[168:169] op_sel_hi:[0,1]
	v_pk_fma_f32 v[126:127], v[2:3], v[118:119], v[94:95]
	v_pk_mul_f32 v[94:95], v[210:211], v[124:125] op_sel_hi:[0,1]
	v_pk_mul_f32 v[96:97], v[210:211], v[114:115] op_sel_hi:[0,1]
	v_pk_fma_f32 v[122:123], v[2:3], v[94:95], v[110:111]
	v_pk_mul_f32 v[94:95], v[188:189], v[170:171] op_sel_hi:[0,1]
	v_pk_fma_f32 v[124:125], v[4:5], v[96:97], v[112:113]
	v_pk_mul_f32 v[96:97], v[188:189], v[120:121] op_sel_hi:[0,1]
	v_pk_fma_f32 v[118:119], v[6:7], v[94:95], v[90:91]
	v_pk_mul_f32 v[90:91], v[210:211], v[190:191] op_sel_hi:[0,1]
	v_pk_fma_f32 v[120:121], v[8:9], v[96:97], v[92:93]
	v_pk_mul_f32 v[92:93], v[210:211], v[192:193] op_sel_hi:[0,1]
	v_pk_fma_f32 v[114:115], v[6:7], v[90:91], v[106:107]
	v_pk_mul_f32 v[90:91], v[188:189], v[172:173] op_sel_hi:[0,1]
	v_pk_fma_f32 v[116:117], v[8:9], v[92:93], v[108:109]
	v_pk_mul_f32 v[92:93], v[188:189], v[174:175] op_sel_hi:[0,1]
	v_pk_fma_f32 v[110:111], v[10:11], v[90:91], v[86:87]
	v_pk_mul_f32 v[86:87], v[210:211], v[194:195] op_sel_hi:[0,1]
	v_pk_fma_f32 v[112:113], v[12:13], v[92:93], v[88:89]
	v_pk_mul_f32 v[88:89], v[210:211], v[196:197] op_sel_hi:[0,1]
	v_pk_fma_f32 v[106:107], v[10:11], v[86:87], v[102:103]
	v_pk_mul_f32 v[86:87], v[188:189], v[176:177] op_sel_hi:[0,1]
	v_pk_fma_f32 v[108:109], v[12:13], v[88:89], v[104:105]
	v_pk_mul_f32 v[88:89], v[188:189], v[178:179] op_sel_hi:[0,1]
	v_pk_fma_f32 v[102:103], v[14:15], v[86:87], v[82:83]
	v_pk_mul_f32 v[82:83], v[210:211], v[198:199] op_sel_hi:[0,1]
	v_pk_fma_f32 v[104:105], v[16:17], v[88:89], v[84:85]
	v_pk_mul_f32 v[84:85], v[210:211], v[200:201] op_sel_hi:[0,1]
	v_pk_fma_f32 v[98:99], v[14:15], v[82:83], v[98:99]
	v_pk_mul_f32 v[82:83], v[188:189], v[180:181] op_sel_hi:[0,1]
	v_pk_fma_f32 v[100:101], v[16:17], v[84:85], v[100:101]
	v_pk_mul_f32 v[84:85], v[188:189], v[154:155] op_sel_hi:[0,1]
	v_pk_fma_f32 v[94:95], v[18:19], v[82:83], v[78:79]
	v_pk_mul_f32 v[78:79], v[210:211], v[202:203] op_sel_hi:[0,1]
	v_pk_fma_f32 v[96:97], v[20:21], v[84:85], v[80:81]
	v_pk_mul_f32 v[80:81], v[210:211], v[152:153] op_sel_hi:[0,1]
	v_pk_fma_f32 v[90:91], v[18:19], v[78:79], v[142:143]
	v_pk_mul_f32 v[78:79], v[188:189], v[182:183] op_sel_hi:[0,1]
	v_pk_fma_f32 v[92:93], v[20:21], v[80:81], v[144:145]
	v_pk_mul_f32 v[80:81], v[188:189], v[158:159] op_sel_hi:[0,1]
	v_pk_fma_f32 v[86:87], v[22:23], v[78:79], v[74:75]
	v_pk_mul_f32 v[74:75], v[210:211], v[204:205] op_sel_hi:[0,1]
	v_pk_fma_f32 v[88:89], v[24:25], v[80:81], v[76:77]
	v_pk_mul_f32 v[76:77], v[210:211], v[156:157] op_sel_hi:[0,1]
	v_pk_fma_f32 v[82:83], v[22:23], v[74:75], v[138:139]
	v_pk_mul_f32 v[74:75], v[188:189], v[184:185] op_sel_hi:[0,1]
	v_pk_fma_f32 v[84:85], v[24:25], v[76:77], v[140:141]
	v_pk_mul_f32 v[76:77], v[188:189], v[162:163] op_sel_hi:[0,1]
	v_pk_fma_f32 v[78:79], v[26:27], v[74:75], v[70:71]
	v_pk_mul_f32 v[70:71], v[210:211], v[206:207] op_sel_hi:[0,1]
	v_pk_fma_f32 v[80:81], v[28:29], v[76:77], v[72:73]
	v_pk_mul_f32 v[72:73], v[210:211], v[160:161] op_sel_hi:[0,1]
	v_pk_fma_f32 v[74:75], v[26:27], v[70:71], v[134:135]
	v_pk_mul_f32 v[70:71], v[188:189], v[186:187] op_sel_hi:[0,1]
	v_pk_fma_f32 v[76:77], v[28:29], v[72:73], v[136:137]
	v_pk_mul_f32 v[72:73], v[188:189], v[166:167] op_sel_hi:[0,1]
	v_pk_fma_f32 v[70:71], v[30:31], v[70:71], v[66:67]
	v_pk_mul_f32 v[66:67], v[210:211], v[208:209] op_sel_hi:[0,1]
	v_pk_fma_f32 v[72:73], v[32:33], v[72:73], v[68:69]
	v_pk_mul_f32 v[68:69], v[210:211], v[164:165] op_sel_hi:[0,1]
; template <int MODE> ...
;     ...
;         if (MODE != 0)
; #pragma unroll
;         for (int rr = 0; rr < RPW; ++rr) { float* xo = xres + (size_t)(m + rr) * DM + lane * 4;
; #pragma unroll
;             for (int k = 0; k < 8; ++k) *(f32x4*)(xo + k * 256) = xv[rr][k]; }
;         if (MODE <= 1) {
;             float rstd[RPW];
; #pragma unroll
;             for (int rr = 0; rr < RPW; ++rr) { float s = 0.f;
; #pragma unroll
;                 for (int k = 0; k < 8; ++k) s += (xv[rr][k][0] * xv[rr][k][0] + xv[rr][k][1] * xv[rr][k][1]) + (xv[rr][k][2] * xv[rr][k][2] + xv[rr][k][3] * xv[rr][k][3]);
;                 rstd[rr] = 1.0f / sqrtf(wave_sum(s) * (1.f / DM) + RMS_EPS); }
	v_pk_fma_f32 v[66:67], v[30:31], v[66:67], v[130:131]
	v_lshl_add_u64 v[130:131], s[78:79], 0, v[146:147]
	v_pk_fma_f32 v[68:69], v[32:33], v[68:69], v[132:133]
	v_add_co_u32_e32 v132, vcc, s19, v130
	global_store_dwordx4 v[130:131], v[126:129], off sc0 sc1
	global_store_dwordx4 v[130:131], v[118:121], off offset:1024 sc0 sc1
	global_store_dwordx4 v[130:131], v[110:113], off offset:2048 sc0 sc1
	global_store_dwordx4 v[130:131], v[102:105], off offset:3072 sc0 sc1
	v_addc_co_u32_e32 v133, vcc, 0, v131, vcc
	v_add_co_u32_e32 v134, vcc, s31, v130
	v_mul_f32_e32 v1, v127, v127
	s_nop 0
	v_addc_co_u32_e32 v135, vcc, 0, v131, vcc
	v_add_co_u32_e32 v130, vcc, s33, v130
	global_store_dwordx4 v[134:135], v[94:97], off offset:-4096 sc0 sc1
	global_store_dwordx4 v[132:133], v[86:89], off offset:1024 sc0 sc1
	global_store_dwordx4 v[132:133], v[78:81], off offset:2048 sc0 sc1
	global_store_dwordx4 v[132:133], v[70:73], off offset:3072 sc0 sc1
	global_store_dwordx4 v[134:135], v[122:125], off sc0 sc1
	global_store_dwordx4 v[134:135], v[114:117], off offset:1024 sc0 sc1
	global_store_dwordx4 v[134:135], v[106:109], off offset:2048 sc0 sc1
	global_store_dwordx4 v[134:135], v[98:101], off offset:3072 sc0 sc1
	v_addc_co_u32_e32 v131, vcc, 0, v131, vcc
	global_store_dwordx4 v[130:131], v[90:93], off sc0 sc1
	global_store_dwordx4 v[130:131], v[82:85], off offset:1024 sc0 sc1
	global_store_dwordx4 v[130:131], v[74:77], off offset:2048 sc0 sc1
	global_store_dwordx4 v[130:131], v[66:69], off offset:3072 sc0 sc1
	v_mul_f32_e32 v130, v129, v129
	v_fmac_f32_e32 v1, v126, v126
	v_fmac_f32_e32 v130, v128, v128
	v_add_f32_e32 v1, v1, v130
	v_mul_f32_e32 v130, v119, v119
	v_mul_f32_e32 v131, v121, v121
	v_fmac_f32_e32 v130, v118, v118
	v_fmac_f32_e32 v131, v120, v120
	v_add_f32_e32 v130, v130, v131
	v_add_f32_e32 v1, v1, v130
	v_mul_f32_e32 v130, v111, v111
	v_mul_f32_e32 v131, v113, v113
	v_fmac_f32_e32 v130, v110, v110
	v_fmac_f32_e32 v131, v112, v112
	v_add_f32_e32 v130, v130, v131
	v_add_f32_e32 v1, v130, v1
	v_mul_f32_e32 v130, v103, v103
	v_mul_f32_e32 v131, v105, v105
	v_fmac_f32_e32 v130, v102, v102
	v_fmac_f32_e32 v131, v104, v104
	v_add_f32_e32 v130, v130, v131
	v_add_f32_e32 v1, v130, v1
	v_mul_f32_e32 v130, v95, v95
	v_mul_f32_e32 v131, v97, v97
	v_fmac_f32_e32 v130, v94, v94
	v_fmac_f32_e32 v131, v96, v96
	v_add_f32_e32 v130, v130, v131
	v_add_f32_e32 v1, v130, v1
	v_mul_f32_e32 v130, v87, v87
	v_mul_f32_e32 v131, v89, v89
	v_fmac_f32_e32 v130, v86, v86
	v_fmac_f32_e32 v131, v88, v88
	v_add_f32_e32 v130, v130, v131
	v_add_f32_e32 v1, v130, v1
	v_mul_f32_e32 v130, v79, v79
	v_mul_f32_e32 v131, v81, v81
	v_fmac_f32_e32 v130, v78, v78
	v_fmac_f32_e32 v131, v80, v80
	v_add_f32_e32 v130, v130, v131
	v_add_f32_e32 v1, v130, v1
	v_mul_f32_e32 v130, v71, v71
	v_mul_f32_e32 v131, v73, v73
	v_fmac_f32_e32 v130, v70, v70
	v_fmac_f32_e32 v131, v72, v72
	v_add_f32_e32 v130, v130, v131
	v_add_f32_e32 v1, v130, v1
	s_add_u32 s78, s78, s26
	s_addc_u32 s79, s79, s27
	v_add_f32_dpp v1, v1, v1 quad_perm:[1,0,3,2] row_mask:0xf bank_mask:0xf bound_ctrl:1
	s_add_u32 s64, s64, s26
	s_addc_u32 s65, s65, s27
	v_add_f32_dpp v1, v1, v1 quad_perm:[2,3,0,1] row_mask:0xf bank_mask:0xf bound_ctrl:1
	s_cmpk_gt_i32 s42, 0x3fff
	s_nop 0
	v_add_f32_dpp v1, v1, v1 row_half_mirror row_mask:0xf bank_mask:0xf bound_ctrl:1
	s_nop 1
	v_add_f32_dpp v1, v1, v1 row_mirror row_mask:0xf bank_mask:0xf bound_ctrl:1
	v_mov_b32_e32 v130, v1
	s_nop 1
	v_permlane16_swap_b32_e32 v1, v130
	v_add_f32_e32 v1, v1, v130
	v_mov_b32_e32 v130, v1
	s_nop 1
	v_permlane32_swap_b32_e32 v1, v130
	v_add_f32_e32 v1, v1, v130
	v_fmamk_f32 v1, v1, 0x3a000000, v218
	v_cmp_gt_f32_e32 vcc, s30, v1
	v_mul_f32_e32 v130, 0x4f800000, v1
	s_nop 0
	v_cndmask_b32_e32 v1, v1, v130, vcc
	v_sqrt_f32_e32 v130, v1
	s_nop 0
	v_add_u32_e32 v131, -1, v130
	v_fma_f32 v132, -v131, v130, v1
	v_cmp_ge_f32_e64 s[40:41], 0, v132
	v_add_u32_e32 v132, 1, v130
	s_nop 0
	v_cndmask_b32_e64 v131, v130, v131, s[40:41]
	v_fma_f32 v130, -v132, v130, v1
	v_cmp_lt_f32_e64 s[40:41], 0, v130
	s_nop 1
	v_cndmask_b32_e64 v130, v131, v132, s[40:41]
	v_mul_f32_e32 v131, 0x37800000, v130
	v_cndmask_b32_e32 v130, v130, v131, vcc
	v_cmp_class_f32_e32 vcc, v1, v215
	s_nop 1
	v_cndmask_b32_e32 v1, v130, v1, vcc
	v_div_scale_f32 v130, s[0:1], v1, v1, 1.0
	v_rcp_f32_e32 v131, v130
	s_nop 0
	v_fma_f32 v132, -v130, v131, 1.0
	v_fmac_f32_e32 v131, v132, v131
	v_div_scale_f32 v132, vcc, 1.0, v1, 1.0
	v_mul_f32_e32 v133, v132, v131
	v_fma_f32 v134, -v130, v133, v132
	v_fmac_f32_e32 v133, v134, v131
	v_fma_f32 v130, -v130, v133, v132
	v_div_fmas_f32 v130, v130, v131, v133
	v_div_fixup_f32 v130, v130, v1, 1.0
	v_mul_f32_e32 v1, v123, v123
	v_mul_f32_e32 v131, v125, v125
	v_fmac_f32_e32 v1, v122, v122
	v_fmac_f32_e32 v131, v124, v124
	v_add_f32_e32 v1, v1, v131
	v_mul_f32_e32 v131, v115, v115
	v_mul_f32_e32 v132, v117, v117
	v_fmac_f32_e32 v131, v114, v114
	v_fmac_f32_e32 v132, v116, v116
	v_add_f32_e32 v131, v131, v132
	v_add_f32_e32 v1, v1, v131
	v_mul_f32_e32 v131, v107, v107
	v_mul_f32_e32 v132, v109, v109
	v_fmac_f32_e32 v131, v106, v106
	v_fmac_f32_e32 v132, v108, v108
	v_add_f32_e32 v131, v131, v132
	v_add_f32_e32 v1, v131, v1
	v_mul_f32_e32 v131, v99, v99
	v_mul_f32_e32 v132, v101, v101
	v_fmac_f32_e32 v131, v98, v98
	v_fmac_f32_e32 v132, v100, v100
	v_add_f32_e32 v131, v131, v132
	v_add_f32_e32 v1, v131, v1
	v_mul_f32_e32 v131, v91, v91
	v_mul_f32_e32 v132, v93, v93
	v_fmac_f32_e32 v131, v90, v90
	v_fmac_f32_e32 v132, v92, v92
	v_add_f32_e32 v131, v131, v132
	v_add_f32_e32 v1, v131, v1
	v_mul_f32_e32 v131, v83, v83
	v_mul_f32_e32 v132, v85, v85
	v_fmac_f32_e32 v131, v82, v82
; __device__ __forceinline__ unsigned pk2(float lo, float hi) { return f2bf(lo) | (f2bf(hi) << 16); }
; template <int MODE> ...
;     ...
;             for (int rr = 0; rr < RPW; ++rr) { float s = 0.f;
; #pragma unroll
;                 for (int k = 0; k < 8; ++k) s += (xv[rr][k][0] * xv[rr][k][0] + xv[rr][k][1] * xv[rr][k][1]) + (xv[rr][k][2] * xv[rr][k][2] + xv[rr][k][3] * xv[rr][k][3]);
;                 rstd[rr] = 1.0f / sqrtf(wave_sum(s) * (1.f / DM) + RMS_EPS); }
; #pragma unroll
;             for (int k = 0; k < 8; ++k) { const f32x4 g = *(const f32x4*)(gpre + k * 256 + lane * 4);
; #pragma unroll
;                 for (int rr = 0; rr < RPW; ++rr) { const f32x4 a = xv[rr][k] * rstd[rr] * g;
;                     v2u o; o.x = pk2(a[0], a[1]); o.y = pk2(a[2], a[3]);
;                     *(v2u*)(h + ((size_t)(k * 4 + (lane >> 4)) * M_TOK + (m + rr)) * 64 + (lane & 15) * 4) = o; } }
	v_fmac_f32_e32 v132, v84, v84
	v_add_f32_e32 v131, v131, v132
	v_add_f32_e32 v1, v131, v1
	v_mul_f32_e32 v131, v75, v75
	v_mul_f32_e32 v132, v77, v77
	v_fmac_f32_e32 v131, v74, v74
	v_fmac_f32_e32 v132, v76, v76
	v_add_f32_e32 v131, v131, v132
	v_add_f32_e32 v1, v131, v1
	v_mul_f32_e32 v131, v67, v67
	v_mul_f32_e32 v132, v69, v69
	v_fmac_f32_e32 v131, v66, v66
	v_fmac_f32_e32 v132, v68, v68
	v_add_f32_e32 v131, v131, v132
	v_add_f32_e32 v1, v131, v1
	s_nop 1
	v_add_f32_dpp v1, v1, v1 quad_perm:[1,0,3,2] row_mask:0xf bank_mask:0xf bound_ctrl:1
	s_nop 1
	v_add_f32_dpp v1, v1, v1 quad_perm:[2,3,0,1] row_mask:0xf bank_mask:0xf bound_ctrl:1
	s_nop 1
	v_add_f32_dpp v1, v1, v1 row_half_mirror row_mask:0xf bank_mask:0xf bound_ctrl:1
	s_nop 1
	v_add_f32_dpp v1, v1, v1 row_mirror row_mask:0xf bank_mask:0xf bound_ctrl:1
	v_mov_b32_e32 v131, v1
	s_nop 1
	v_permlane16_swap_b32_e32 v1, v131
	v_add_f32_e32 v1, v1, v131
	v_mov_b32_e32 v131, v1
	s_nop 1
	v_permlane32_swap_b32_e32 v1, v131
	v_add_f32_e32 v1, v1, v131
	v_fmamk_f32 v1, v1, 0x3a000000, v218
	v_cmp_gt_f32_e32 vcc, s30, v1
	v_mul_f32_e32 v131, 0x4f800000, v1
	s_nop 0
	v_cndmask_b32_e32 v1, v1, v131, vcc
	v_sqrt_f32_e32 v131, v1
	s_nop 0
	v_add_u32_e32 v132, -1, v131
	v_fma_f32 v133, -v132, v131, v1
	v_cmp_ge_f32_e64 s[40:41], 0, v133
	v_add_u32_e32 v133, 1, v131
	s_nop 0
	v_cndmask_b32_e64 v132, v131, v132, s[40:41]
	v_fma_f32 v131, -v133, v131, v1
	v_cmp_lt_f32_e64 s[40:41], 0, v131
	s_nop 1
	v_cndmask_b32_e64 v131, v132, v133, s[40:41]
	v_mul_f32_e32 v132, 0x37800000, v131
	v_cndmask_b32_e32 v131, v131, v132, vcc
	v_cmp_class_f32_e32 vcc, v1, v215
	s_nop 1
	v_cndmask_b32_e32 v1, v131, v1, vcc
	v_div_scale_f32 v131, s[0:1], v1, v1, 1.0
	v_rcp_f32_e32 v132, v131
	s_mov_b32 s0, 0x4800000
	v_fma_f32 v133, -v131, v132, 1.0
	v_fmac_f32_e32 v132, v133, v132
	v_div_scale_f32 v133, vcc, 1.0, v1, 1.0
	v_mul_f32_e32 v134, v133, v132
	v_fma_f32 v135, -v131, v134, v133
	v_fmac_f32_e32 v134, v135, v132
	v_fma_f32 v131, -v131, v134, v133
	v_div_fmas_f32 v131, v131, v132, v134
	v_pk_mul_f32 v[126:127], v[126:127], v[130:131] op_sel_hi:[1,0]
	v_div_fixup_f32 v132, v131, v1, 1.0
	v_pk_mul_f32 v[126:127], v[46:47], v[126:127]
	v_pk_mul_f32 v[128:129], v[128:129], v[130:131] op_sel_hi:[1,0]
	v_bfe_u32 v1, v126, 16, 1
	v_add3_u32 v1, v126, v1, s63
	v_bfe_u32 v126, v127, 16, 1
	v_pk_mul_f32 v[128:129], v[48:49], v[128:129]
	v_lshrrev_b32_e32 v1, 16, v1
	v_add3_u32 v126, v127, v126, s63
	v_and_or_b32 v126, v126, s60, v1
	v_bfe_u32 v1, v128, 16, 1
	v_add3_u32 v1, v128, v1, s63
	v_bfe_u32 v127, v129, 16, 1
	v_pk_mul_f32 v[122:123], v[122:123], v[132:133] op_sel_hi:[1,0]
	v_lshrrev_b32_e32 v1, 16, v1
	v_add3_u32 v127, v129, v127, s63
	v_pk_mul_f32 v[122:123], v[46:47], v[122:123]
	v_and_or_b32 v127, v127, s60, v1
	v_bfe_u32 v1, v122, 16, 1
	v_pk_mul_f32 v[124:125], v[124:125], v[132:133] op_sel_hi:[1,0]
	v_add3_u32 v1, v122, v1, s63
	v_bfe_u32 v122, v123, 16, 1
	v_pk_mul_f32 v[124:125], v[48:49], v[124:125]
	v_lshrrev_b32_e32 v1, 16, v1
	v_add3_u32 v122, v123, v122, s63
	v_and_or_b32 v122, v122, s60, v1
	v_bfe_u32 v1, v124, 16, 1
	v_add3_u32 v1, v124, v1, s63
	v_bfe_u32 v123, v125, 16, 1
	v_pk_mul_f32 v[118:119], v[118:119], v[130:131] op_sel_hi:[1,0]
	v_lshrrev_b32_e32 v1, 16, v1
	v_add3_u32 v123, v125, v123, s63
	v_pk_mul_f32 v[118:119], v[34:35], v[118:119]
	v_and_or_b32 v123, v123, s60, v1
	v_bfe_u32 v1, v118, 16, 1
	v_pk_mul_f32 v[120:121], v[120:121], v[130:131] op_sel_hi:[1,0]
	v_add3_u32 v1, v118, v1, s63
	v_bfe_u32 v118, v119, 16, 1
	v_pk_mul_f32 v[120:121], v[36:37], v[120:121]
	v_lshrrev_b32_e32 v1, 16, v1
	v_add3_u32 v118, v119, v118, s63
	v_and_or_b32 v118, v118, s60, v1
	v_bfe_u32 v1, v120, 16, 1
	v_add3_u32 v1, v120, v1, s63
	v_bfe_u32 v119, v121, 16, 1
	v_pk_mul_f32 v[114:115], v[114:115], v[132:133] op_sel_hi:[1,0]
	v_lshrrev_b32_e32 v1, 16, v1
	v_add3_u32 v119, v121, v119, s63
	v_pk_mul_f32 v[114:115], v[34:35], v[114:115]
	v_and_or_b32 v119, v119, s60, v1
	v_bfe_u32 v1, v114, 16, 1
	v_pk_mul_f32 v[116:117], v[116:117], v[132:133] op_sel_hi:[1,0]
	v_add3_u32 v1, v114, v1, s63
	v_bfe_u32 v114, v115, 16, 1
	v_pk_mul_f32 v[116:117], v[36:37], v[116:117]
	v_lshrrev_b32_e32 v1, 16, v1
	v_add3_u32 v114, v115, v114, s63
	v_and_or_b32 v114, v114, s60, v1
	v_bfe_u32 v1, v116, 16, 1
	v_add3_u32 v1, v116, v1, s63
	v_bfe_u32 v115, v117, 16, 1
	v_pk_mul_f32 v[110:111], v[110:111], v[130:131] op_sel_hi:[1,0]
	v_lshrrev_b32_e32 v1, 16, v1
	v_add3_u32 v115, v117, v115, s63
	v_pk_mul_f32 v[110:111], v[38:39], v[110:111]
	v_and_or_b32 v115, v115, s60, v1
	v_bfe_u32 v1, v110, 16, 1
	v_pk_mul_f32 v[112:113], v[112:113], v[130:131] op_sel_hi:[1,0]
	v_add3_u32 v1, v110, v1, s63
	v_bfe_u32 v110, v111, 16, 1
	v_pk_mul_f32 v[112:113], v[40:41], v[112:113]
	v_lshrrev_b32_e32 v1, 16, v1
	v_add3_u32 v110, v111, v110, s63
	v_and_or_b32 v110, v110, s60, v1
	v_bfe_u32 v1, v112, 16, 1
	v_add3_u32 v1, v112, v1, s63
	v_bfe_u32 v111, v113, 16, 1
	v_pk_mul_f32 v[106:107], v[106:107], v[132:133] op_sel_hi:[1,0]
	v_lshrrev_b32_e32 v1, 16, v1
	v_add3_u32 v111, v113, v111, s63
	v_pk_mul_f32 v[106:107], v[38:39], v[106:107]
	v_and_or_b32 v111, v111, s60, v1
	v_bfe_u32 v1, v106, 16, 1
	v_pk_mul_f32 v[108:109], v[108:109], v[132:133] op_sel_hi:[1,0]
	v_add3_u32 v1, v106, v1, s63
	v_bfe_u32 v106, v107, 16, 1
	v_pk_mul_f32 v[108:109], v[40:41], v[108:109]
	v_lshrrev_b32_e32 v1, 16, v1
	v_add3_u32 v106, v107, v106, s63
	v_and_or_b32 v106, v106, s60, v1
	v_bfe_u32 v1, v108, 16, 1
	v_add3_u32 v1, v108, v1, s63
	v_bfe_u32 v107, v109, 16, 1
	v_pk_mul_f32 v[102:103], v[102:103], v[130:131] op_sel_hi:[1,0]
	v_lshrrev_b32_e32 v1, 16, v1
; __device__ __forceinline__ unsigned pk2(float lo, float hi) { return f2bf(lo) | (f2bf(hi) << 16); }
; template <int MODE> ...
;     ...
; #pragma unroll
;             for (int k = 0; k < 8; ++k) { const f32x4 g = *(const f32x4*)(gpre + k * 256 + lane * 4);
; #pragma unroll
;                 for (int rr = 0; rr < RPW; ++rr) { const f32x4 a = xv[rr][k] * rstd[rr] * g;
;                     v2u o; o.x = pk2(a[0], a[1]); o.y = pk2(a[2], a[3]);
;                     *(v2u*)(h + ((size_t)(k * 4 + (lane >> 4)) * M_TOK + (m + rr)) * 64 + (lane & 15) * 4) = o; } }
	v_add3_u32 v107, v109, v107, s63
	v_pk_mul_f32 v[102:103], v[42:43], v[102:103]
	v_and_or_b32 v107, v107, s60, v1
	v_bfe_u32 v1, v102, 16, 1
	v_pk_mul_f32 v[104:105], v[104:105], v[130:131] op_sel_hi:[1,0]
	v_add3_u32 v1, v102, v1, s63
	v_bfe_u32 v102, v103, 16, 1
	v_pk_mul_f32 v[104:105], v[44:45], v[104:105]
	v_lshrrev_b32_e32 v1, 16, v1
	v_add3_u32 v102, v103, v102, s63
	v_and_or_b32 v102, v102, s60, v1
	v_bfe_u32 v1, v104, 16, 1
	v_add3_u32 v1, v104, v1, s63
	v_bfe_u32 v103, v105, 16, 1
	v_pk_mul_f32 v[98:99], v[98:99], v[132:133] op_sel_hi:[1,0]
	v_lshrrev_b32_e32 v1, 16, v1
	v_add3_u32 v103, v105, v103, s63
	v_pk_mul_f32 v[98:99], v[42:43], v[98:99]
	v_and_or_b32 v103, v103, s60, v1
	v_bfe_u32 v1, v98, 16, 1
	v_pk_mul_f32 v[100:101], v[100:101], v[132:133] op_sel_hi:[1,0]
	v_add3_u32 v1, v98, v1, s63
	v_bfe_u32 v98, v99, 16, 1
	v_pk_mul_f32 v[100:101], v[44:45], v[100:101]
	v_lshrrev_b32_e32 v1, 16, v1
	v_add3_u32 v98, v99, v98, s63
	v_and_or_b32 v98, v98, s60, v1
	v_bfe_u32 v1, v100, 16, 1
	v_add3_u32 v1, v100, v1, s63
	v_bfe_u32 v99, v101, 16, 1
	v_pk_mul_f32 v[94:95], v[94:95], v[130:131] op_sel_hi:[1,0]
	v_lshrrev_b32_e32 v1, 16, v1
	v_add3_u32 v99, v101, v99, s63
	v_pk_mul_f32 v[94:95], v[50:51], v[94:95]
	v_and_or_b32 v99, v99, s60, v1
	v_bfe_u32 v1, v94, 16, 1
	v_pk_mul_f32 v[96:97], v[96:97], v[130:131] op_sel_hi:[1,0]
	v_add3_u32 v1, v94, v1, s63
	v_bfe_u32 v94, v95, 16, 1
	v_pk_mul_f32 v[96:97], v[52:53], v[96:97]
	v_lshrrev_b32_e32 v1, 16, v1
	v_add3_u32 v94, v95, v94, s63
	v_and_or_b32 v94, v94, s60, v1
	v_bfe_u32 v1, v96, 16, 1
	v_add3_u32 v1, v96, v1, s63
	v_bfe_u32 v95, v97, 16, 1
	v_pk_mul_f32 v[90:91], v[90:91], v[132:133] op_sel_hi:[1,0]
	v_lshrrev_b32_e32 v1, 16, v1
	v_add3_u32 v95, v97, v95, s63
	v_pk_mul_f32 v[90:91], v[50:51], v[90:91]
	v_and_or_b32 v95, v95, s60, v1
	v_bfe_u32 v1, v90, 16, 1
	v_pk_mul_f32 v[92:93], v[92:93], v[132:133] op_sel_hi:[1,0]
	v_add3_u32 v1, v90, v1, s63
	v_bfe_u32 v90, v91, 16, 1
	v_pk_mul_f32 v[92:93], v[52:53], v[92:93]
	v_lshrrev_b32_e32 v1, 16, v1
	v_add3_u32 v90, v91, v90, s63
	v_and_or_b32 v90, v90, s60, v1
	v_bfe_u32 v1, v92, 16, 1
	v_add3_u32 v1, v92, v1, s63
	v_bfe_u32 v91, v93, 16, 1
	v_pk_mul_f32 v[86:87], v[86:87], v[130:131] op_sel_hi:[1,0]
	v_lshrrev_b32_e32 v1, 16, v1
	v_add3_u32 v91, v93, v91, s63
	v_pk_mul_f32 v[86:87], v[54:55], v[86:87]
	v_and_or_b32 v91, v91, s60, v1
	v_bfe_u32 v1, v86, 16, 1
	v_pk_mul_f32 v[88:89], v[88:89], v[130:131] op_sel_hi:[1,0]
	v_add3_u32 v1, v86, v1, s63
	v_bfe_u32 v86, v87, 16, 1
	v_pk_mul_f32 v[88:89], v[56:57], v[88:89]
	v_lshrrev_b32_e32 v1, 16, v1
	v_add3_u32 v86, v87, v86, s63
	v_and_or_b32 v86, v86, s60, v1
	v_bfe_u32 v1, v88, 16, 1
	v_add3_u32 v1, v88, v1, s63
	v_bfe_u32 v87, v89, 16, 1
	v_pk_mul_f32 v[82:83], v[82:83], v[132:133] op_sel_hi:[1,0]
	v_lshrrev_b32_e32 v1, 16, v1
	v_add3_u32 v87, v89, v87, s63
	v_pk_mul_f32 v[82:83], v[54:55], v[82:83]
	v_and_or_b32 v87, v87, s60, v1
	v_bfe_u32 v1, v82, 16, 1
	v_pk_mul_f32 v[84:85], v[84:85], v[132:133] op_sel_hi:[1,0]
	v_add3_u32 v1, v82, v1, s63
	v_bfe_u32 v82, v83, 16, 1
	v_pk_mul_f32 v[84:85], v[56:57], v[84:85]
	v_lshrrev_b32_e32 v1, 16, v1
	v_add3_u32 v82, v83, v82, s63
	v_and_or_b32 v82, v82, s60, v1
	v_bfe_u32 v1, v84, 16, 1
	v_add3_u32 v1, v84, v1, s63
	v_bfe_u32 v83, v85, 16, 1
	v_pk_mul_f32 v[78:79], v[78:79], v[130:131] op_sel_hi:[1,0]
	v_lshrrev_b32_e32 v1, 16, v1
	v_add3_u32 v83, v85, v83, s63
	v_pk_mul_f32 v[78:79], v[58:59], v[78:79]
	v_and_or_b32 v83, v83, s60, v1
	v_bfe_u32 v1, v78, 16, 1
	v_pk_mul_f32 v[80:81], v[80:81], v[130:131] op_sel_hi:[1,0]
	v_add3_u32 v1, v78, v1, s63
	v_bfe_u32 v78, v79, 16, 1
	v_pk_mul_f32 v[80:81], v[60:61], v[80:81]
	v_lshrrev_b32_e32 v1, 16, v1
	v_add3_u32 v78, v79, v78, s63
	v_and_or_b32 v78, v78, s60, v1
; __device__ __forceinline__ unsigned pk2(float lo, float hi) { return f2bf(lo) | (f2bf(hi) << 16); }
; template <int MODE> ...
;     ...
; #pragma unroll
;             for (int k = 0; k < 8; ++k) { const f32x4 g = *(const f32x4*)(gpre + k * 256 + lane * 4);
; #pragma unroll
;                 for (int rr = 0; rr < RPW; ++rr) { const f32x4 a = xv[rr][k] * rstd[rr] * g;
;                     v2u o; o.x = pk2(a[0], a[1]); o.y = pk2(a[2], a[3]);
;                     *(v2u*)(h + ((size_t)(k * 4 + (lane >> 4)) * M_TOK + (m + rr)) * 64 + (lane & 15) * 4) = o; } }
	v_bfe_u32 v1, v80, 16, 1
	v_add3_u32 v1, v80, v1, s63
	v_bfe_u32 v79, v81, 16, 1
	v_pk_mul_f32 v[74:75], v[74:75], v[132:133] op_sel_hi:[1,0]
	v_lshrrev_b32_e32 v1, 16, v1
	v_add3_u32 v79, v81, v79, s63
	v_pk_mul_f32 v[74:75], v[58:59], v[74:75]
	v_and_or_b32 v79, v79, s60, v1
	v_bfe_u32 v1, v74, 16, 1
	v_pk_mul_f32 v[76:77], v[76:77], v[132:133] op_sel_hi:[1,0]
	v_add3_u32 v1, v74, v1, s63
	v_bfe_u32 v74, v75, 16, 1
	v_lshl_add_u64 v[128:129], v[148:149], 0, s[46:47]
	v_pk_mul_f32 v[76:77], v[60:61], v[76:77]
	v_lshrrev_b32_e32 v1, 16, v1
	v_add3_u32 v74, v75, v74, s63
	v_add_co_u32_e32 v134, vcc, s0, v128
	v_and_or_b32 v74, v74, s60, v1
	v_bfe_u32 v1, v76, 16, 1
	v_addc_co_u32_e32 v135, vcc, 0, v129, vcc
	s_mov_b32 s0, 0x5000000
	v_add3_u32 v1, v76, v1, s63
	v_bfe_u32 v75, v77, 16, 1
	v_pk_mul_f32 v[70:71], v[70:71], v[130:131] op_sel_hi:[1,0]
	v_add_co_u32_e32 v120, vcc, s0, v128
	v_lshrrev_b32_e32 v1, 16, v1
	v_add3_u32 v75, v77, v75, s63
	v_pk_mul_f32 v[70:71], v[62:63], v[70:71]
	v_addc_co_u32_e32 v121, vcc, 0, v129, vcc
	s_mov_b32 s0, 0x5800000
	v_and_or_b32 v75, v75, s60, v1
	v_bfe_u32 v1, v70, 16, 1
	v_add_co_u32_e32 v112, vcc, s0, v128
	v_pk_mul_f32 v[72:73], v[72:73], v[130:131] op_sel_hi:[1,0]
	v_add3_u32 v1, v70, v1, s63
	v_bfe_u32 v70, v71, 16, 1
	v_addc_co_u32_e32 v113, vcc, 0, v129, vcc
	s_mov_b32 s0, 0x6000000
	v_pk_mul_f32 v[72:73], v[64:65], v[72:73]
	v_lshrrev_b32_e32 v1, 16, v1
	v_add3_u32 v70, v71, v70, s63
	v_add_co_u32_e32 v104, vcc, s0, v128
	v_and_or_b32 v70, v70, s60, v1
	v_bfe_u32 v1, v72, 16, 1
	v_addc_co_u32_e32 v105, vcc, 0, v129, vcc
	s_mov_b32 s0, 0x6800000
	v_add3_u32 v1, v72, v1, s63
	v_bfe_u32 v71, v73, 16, 1
	v_pk_mul_f32 v[66:67], v[66:67], v[132:133] op_sel_hi:[1,0]
	v_add_co_u32_e32 v96, vcc, s0, v128
	v_lshrrev_b32_e32 v1, 16, v1
	v_add3_u32 v71, v73, v71, s63
	v_pk_mul_f32 v[66:67], v[62:63], v[66:67]
	v_addc_co_u32_e32 v97, vcc, 0, v129, vcc
	s_mov_b32 s0, 0x7000000
	v_and_or_b32 v71, v71, s60, v1
	v_bfe_u32 v1, v66, 16, 1
	v_add_co_u32_e32 v88, vcc, s0, v128
	v_pk_mul_f32 v[68:69], v[68:69], v[132:133] op_sel_hi:[1,0]
	v_add3_u32 v1, v66, v1, s63
	v_bfe_u32 v66, v67, 16, 1
	v_addc_co_u32_e32 v89, vcc, 0, v129, vcc
	s_mov_b32 s0, 0x7800000
	v_pk_mul_f32 v[68:69], v[64:65], v[68:69]
	v_lshrrev_b32_e32 v1, 16, v1
	v_add3_u32 v66, v67, v66, s63
	v_add_co_u32_e32 v80, vcc, s0, v128
	v_and_or_b32 v66, v66, s60, v1
	v_bfe_u32 v1, v68, 16, 1
	v_addc_co_u32_e32 v81, vcc, 0, v129, vcc
	s_brev_b32 s0, 16
	v_add3_u32 v1, v68, v1, s63
	v_bfe_u32 v67, v69, 16, 1
	v_add_co_u32_e32 v72, vcc, s0, v128
	v_lshrrev_b32_e32 v1, 16, v1
	v_add3_u32 v67, v69, v67, s63
	v_addc_co_u32_e32 v73, vcc, 0, v129, vcc
	v_and_or_b32 v67, v67, s60, v1
	v_lshl_add_u64 v[148:149], v[148:149], 0, s[20:21]
	global_store_dwordx2 v[134:135], v[126:127], off sc0 sc1
	global_store_dwordx2 v[134:135], v[122:123], off offset:128 sc0 sc1
	global_store_dwordx2 v[120:121], v[118:119], off sc0 sc1
	global_store_dwordx2 v[120:121], v[114:115], off offset:128 sc0 sc1
	global_store_dwordx2 v[112:113], v[110:111], off sc0 sc1
	global_store_dwordx2 v[112:113], v[106:107], off offset:128 sc0 sc1
	global_store_dwordx2 v[104:105], v[102:103], off sc0 sc1
	global_store_dwordx2 v[104:105], v[98:99], off offset:128 sc0 sc1
	global_store_dwordx2 v[96:97], v[94:95], off sc0 sc1
	global_store_dwordx2 v[96:97], v[90:91], off offset:128 sc0 sc1
	global_store_dwordx2 v[88:89], v[86:87], off sc0 sc1
	global_store_dwordx2 v[88:89], v[82:83], off offset:128 sc0 sc1
	global_store_dwordx2 v[80:81], v[78:79], off sc0 sc1
	global_store_dwordx2 v[80:81], v[74:75], off offset:128 sc0 sc1
	global_store_dwordx2 v[72:73], v[70:71], off sc0 sc1
	global_store_dwordx2 v[72:73], v[66:67], off offset:128 sc0 sc1
	s_cbranch_scc0 .LBB0_225
